# conv_edge rewritten by hand: all nine loads of a unit issued together instead of one-load-one-wait chain
# baseline (speedup 1.0000x reference)
.LBB0_813:
	s_cmp_lt_i32 s78, 6
	s_cselect_b64 s[6:7], -1, 0
	s_cmp_gt_i32 s79, 5
	s_cselect_b64 s[0:1], -1, 0
	s_and_b64 s[0:1], s[6:7], s[0:1]
	s_andn2_b64 vcc, exec, s[0:1]
	s_cbranch_vccnz .LBB0_882
	s_add_u32 s10, s76, 0xfd00000
	s_addc_u32 s11, s77, 0
	s_add_u32 s8, s76, 0xc500000
	v_writelane_b32 v242, s85, 60
	s_addc_u32 s9, s77, 0
	s_ashr_i32 s85, s64, 31
	s_ashr_i32 s3, s2, 31
	s_mov_b64 s[60:61], s[64:65]
	v_readlane_b32 s12, v242, 37
	v_readlane_b32 s48, v242, 15
	v_readlane_b32 s49, v242, 16
	v_readlane_b32 s50, v242, 17
	v_readlane_b32 s51, v242, 18
	v_lshlrev_b32_e32 v16, 2, v184
	s_cmp_gt_u32 s12, 2
	s_cbranch_scc1 .LBB0_841
	s_add_u32 s34, s48, 0x1000
	s_addc_u32 s35, s49, 0
	s_add_u32 s36, s48, 0x2000
	s_addc_u32 s37, s49, 0
	s_add_u32 s38, s48, 0x3000
	s_addc_u32 s39, s49, 0
	s_mov_b32 s28, s2
.Lce_loop:
	s_cmp_gt_i32 s28, 0x1ff
	s_cbranch_scc1 .LBB0_841
	s_and_b32 s20, s28, 7
	s_lshl_b32 s20, s20, 6
	s_lshr_b32 s21, s28, 3
	s_add_u32 s20, s20, s21
	s_lshr_b32 s21, s20, 5
	s_lshl_b32 s21, s21, 2
	s_and_b32 s22, s20, 3
	s_add_u32 s21, s21, s22
	s_lshr_b32 s22, s20, 3
	s_and_b32 s22, s22, 3
	s_lshl_b32 s22, s22, 8
	v_or_b32_e32 v10, s22, v16
	v_lshlrev_b32_e32 v11, 2, v10
	v_lshlrev_b32_e32 v17, 1, v10
	s_mul_i32 s23, s21, 6
	s_add_u32 s23, s23, s12
	s_sub_u32 s23, s23, 3
	s_max_i32 s24, s23, 0
	s_lshl_b32 s24, s24, 11
	s_add_u32 s26, s10, s24
	s_addc_u32 s27, s11, 0
	s_add_i32 s24, s23, 1
	s_max_i32 s24, s24, 0
	s_lshl_b32 s24, s24, 11
	s_add_u32 s30, s10, s24
	s_addc_u32 s31, s11, 0
	s_add_i32 s24, s23, 2
	s_max_i32 s24, s24, 0
	s_lshl_b32 s24, s24, 11
	s_add_u32 s40, s10, s24
	s_addc_u32 s41, s11, 0
	s_add_i32 s24, s23, 3
	s_lshl_b32 s24, s24, 11
	s_add_u32 s42, s10, s24
	s_addc_u32 s43, s11, 0
	s_lshl_b32 s24, s21, 8
	s_add_u32 s24, s24, s12
	s_lshl_b32 s24, s24, 11
	s_add_u32 s44, s8, s24
	s_addc_u32 s45, s9, 0
	s_and_b32 s46, s21, 15
	s_sub_u32 s47, 3, s12
	s_cmp_eq_u32 s46, 0
	s_cselect_b32 s46, s47, 0
	global_load_dwordx4 v[0:3], v11, s[50:51]
	global_load_dwordx2 v[12:13], v17, s[26:27]
	global_load_dwordx4 v[4:7], v11, s[48:49]
	global_load_dwordx2 v[14:15], v17, s[30:31]
	global_load_dwordx4 v[18:21], v11, s[34:35]
	global_load_dwordx2 v[8:9], v17, s[40:41]
	global_load_dwordx4 v[22:25], v11, s[36:37]
	global_load_dwordx2 v[30:31], v17, s[42:43]
	global_load_dwordx4 v[26:29], v11, s[38:39]
	s_waitcnt vmcnt(0)
	s_cmp_ge_u32 s46, 1
	s_cbranch_scc1 .Lce_t1
	v_lshlrev_b32_e32 v32, 16, v12
	v_and_b32_e32 v33, 0xffff0000, v12
	v_lshlrev_b32_e32 v34, 16, v13
	v_and_b32_e32 v35, 0xffff0000, v13
	v_pk_fma_f32 v[2:3], v[6:7], v[34:35], v[2:3]
	v_pk_fma_f32 v[0:1], v[4:5], v[32:33], v[0:1]
.Lce_t1:
	s_cmp_ge_u32 s46, 2
	s_cbranch_scc1 .Lce_t2
	v_lshlrev_b32_e32 v32, 16, v14
	v_and_b32_e32 v33, 0xffff0000, v14
	v_lshlrev_b32_e32 v34, 16, v15
	v_and_b32_e32 v35, 0xffff0000, v15
	v_pk_fma_f32 v[2:3], v[20:21], v[34:35], v[2:3]
	v_pk_fma_f32 v[0:1], v[18:19], v[32:33], v[0:1]
.Lce_t2:
	s_cmp_ge_u32 s46, 3
	s_cbranch_scc1 .Lce_t3
	v_lshlrev_b32_e32 v32, 16, v8
	v_and_b32_e32 v33, 0xffff0000, v8
	v_lshlrev_b32_e32 v34, 16, v9
	v_and_b32_e32 v35, 0xffff0000, v9
	v_pk_fma_f32 v[2:3], v[24:25], v[34:35], v[2:3]
	v_pk_fma_f32 v[0:1], v[22:23], v[32:33], v[0:1]
.Lce_t3:
	v_lshlrev_b32_e32 v32, 16, v30
	v_and_b32_e32 v33, 0xffff0000, v30
	v_lshlrev_b32_e32 v34, 16, v31
	v_and_b32_e32 v35, 0xffff0000, v31
	v_pk_fma_f32 v[2:3], v[28:29], v[34:35], v[2:3]
	v_pk_fma_f32 v[0:1], v[26:27], v[32:33], v[0:1]
	s_nop 1
	v_cvt_pk_bf16_f32 v0, v0, v1
	v_cvt_pk_bf16_f32 v1, v2, v3
	s_nop 0
	global_store_dwordx2 v17, v[0:1], s[44:45]
	s_add_u32 s28, s28, s64
	s_branch .Lce_loop
